# V1: proj K-loop phases 3+4 and 7+8 merged (2 fewer barrier pairs per 2 K-tiles), counted vmcnt relaxed
# speedup vs baseline: 1.0389x; 1.0389x over previous
; #define PG8_WAIT_V(n) asm volatile("s_waitcnt vmcnt(" #n ")" ::: "memory")
; #define PG8_WAIT_L(n) asm volatile("s_waitcnt lgkmcnt(" #n ")" ::: "memory")
; #define PG8_BAR __builtin_amdgcn_s_barrier()
; #define PG8_SCHED __builtin_amdgcn_sched_barrier(0)
; template <class Epi, class AddrA, class AddrB>
; __device__ __forceinline__ void gemm_phase(const Sched S, const int lda, const int ldb, const int K, const AddrA addrA,
;                                            const AddrB addrB, const Epi E) {
;     ...
;     for (int t = 0; t < nt; t += 2) {
;       const bool last = (t == nt - 2);
;       const char* a1 = cA + (size_t)(t + 1) * kstep;
;       const char* a2 = last ? nA : cA + (size_t)(t + 2) * kstep;
;       const char* b2 = last ? nB : cB + (size_t)(t + 2) * kstep;
;       const char* a3 = a2 + kstep;
;       const char* b3 = b2 + kstep;
;       PG8_LDB(B0, 0, 0); PG8_SCHED; PG8_LDA(At, 0, 0); PG8_STAGE(PG8_SA(1, 1), a1 + hstepA, voffA);
;       PG8_WAIT_L(8); PG8_BAR; PG8_WAIT_L(0); PG8_MMA(0, 0, At, B0); PG8_BAR; PG8_SCHED;
;       PG8_LDB(B1, 0, 1); PG8_STAGE(PG8_SB(0, 0), b2, voffB);
;       PG8_BAR; PG8_WAIT_L(0); PG8_MMA(0, 1, At, B1); PG8_BAR;
;       PG8_LDA(At, 0, 1); PG8_STAGE(PG8_SA(0, 0), a2, voffA);
;       PG8_BAR; PG8_WAIT_L(0); PG8_MMA(1, 0, At, B0); PG8_BAR; PG8_SCHED;
;       PG8_STAGE(PG8_SB(0, 1), b2 + hstepB, voffB);
;       PG8_WAIT_V(6); PG8_BAR; PG8_MMA(1, 1, At, B1); PG8_BAR;
.LBB0_109:
	s_add_u32 s14, s12, 0xfff80080
	s_addc_u32 s15, s13, -1
	s_add_i32 s40, 0, 0x10000
	v_add_u32_e32 v142, s40, v145
	ds_read_b128 v[148:151], v142
	ds_read_b128 v[152:155], v142 offset:1024
	ds_read_b128 v[156:159], v142 offset:2048
	ds_read_b128 v[160:163], v142 offset:3072
	s_cmp_eq_u32 s39, 28
	s_cselect_b32 s17, s1, s15
	s_cselect_b32 s16, s11, s14
	s_cselect_b32 s15, s3, s38
	s_cselect_b32 s14, s36, s37
	v_lshl_add_u64 v[142:143], s[12:13], 0, v[140:141]
	s_add_i32 m0, s24, 0xc000
	ds_read_b128 v[168:171], v146
	ds_read_b128 v[172:175], v146 offset:1024
	ds_read_b128 v[176:179], v146 offset:2048
	ds_read_b128 v[180:183], v146 offset:3072
	ds_read_b128 v[184:187], v146 offset:4096
	ds_read_b128 v[188:191], v146 offset:5120
	ds_read_b128 v[192:195], v146 offset:6144
	ds_read_b128 v[212:215], v146 offset:7168
	global_load_lds_dwordx4 v[142:143], off
	v_lshl_add_u64 v[142:143], s[12:13], 0, v[138:139]
	s_add_i32 m0, s24, 0xe000
	s_nop 0
	global_load_lds_dwordx4 v[142:143], off
	s_waitcnt lgkmcnt(8)
	s_barrier
	s_waitcnt lgkmcnt(0)
	s_setprio 1
	s_waitcnt lgkmcnt(0)
	v_mfma_f32_16x16x32_bf16 v[128:131], v[148:151], v[168:171], v[128:131]
	v_mfma_f32_16x16x32_bf16 v[124:127], v[156:159], v[168:171], v[124:127]
	v_mfma_f32_16x16x32_bf16 v[120:123], v[148:151], v[176:179], v[120:123]
	v_mfma_f32_16x16x32_bf16 v[112:115], v[156:159], v[176:179], v[112:115]
	v_mfma_f32_16x16x32_bf16 v[104:107], v[148:151], v[184:187], v[104:107]
	v_mfma_f32_16x16x32_bf16 v[96:99], v[156:159], v[184:187], v[96:99]
	v_mfma_f32_16x16x32_bf16 v[88:91], v[148:151], v[192:195], v[88:91]
	v_mfma_f32_16x16x32_bf16 v[80:83], v[156:159], v[192:195], v[80:83]
	v_mfma_f32_16x16x32_bf16 v[128:131], v[152:155], v[172:175], v[128:131]
	v_mfma_f32_16x16x32_bf16 v[124:127], v[160:163], v[172:175], v[124:127]
	v_mfma_f32_16x16x32_bf16 v[120:123], v[152:155], v[180:183], v[120:123]
	v_mfma_f32_16x16x32_bf16 v[112:115], v[160:163], v[180:183], v[112:115]
	v_mfma_f32_16x16x32_bf16 v[104:107], v[152:155], v[188:191], v[104:107]
	v_mfma_f32_16x16x32_bf16 v[96:99], v[160:163], v[188:191], v[96:99]
	v_mfma_f32_16x16x32_bf16 v[88:91], v[152:155], v[212:215], v[88:91]
	v_mfma_f32_16x16x32_bf16 v[80:83], v[160:163], v[212:215], v[80:83]
	s_setprio 0
	s_barrier
	s_add_i32 s42, 0, 0x14000
	v_add_u32_e32 v142, s42, v145
	s_add_i32 s40, s40, s19
	ds_read_b128 v[216:219], v142
	ds_read_b128 v[220:223], v142 offset:1024
	ds_read_b128 v[224:227], v142 offset:2048
	ds_read_b128 v[228:231], v142 offset:3072
	v_lshl_add_u64 v[142:143], s[14:15], 0, v[134:135]
	s_mov_b32 m0, s40
	v_lshl_add_u64 v[196:197], s[14:15], 0, v[0:1]
	global_load_lds_dwordx4 v[142:143], off
	s_add_i32 m0, s40, 0x2000
	s_nop 0
	global_load_lds_dwordx4 v[196:197], off
	s_waitcnt vmcnt(10)
	s_waitcnt lgkmcnt(0)
	s_barrier
	s_waitcnt lgkmcnt(0)
	s_setprio 1
	s_waitcnt lgkmcnt(0)
	v_mfma_f32_16x16x32_bf16 v[116:119], v[216:219], v[168:171], v[116:119]
	v_mfma_f32_16x16x32_bf16 v[108:111], v[224:227], v[168:171], v[108:111]
	v_mfma_f32_16x16x32_bf16 v[100:103], v[216:219], v[176:179], v[100:103]
	v_mfma_f32_16x16x32_bf16 v[92:95], v[224:227], v[176:179], v[92:95]
	v_mfma_f32_16x16x32_bf16 v[84:87], v[216:219], v[184:187], v[84:87]
	v_mfma_f32_16x16x32_bf16 v[76:79], v[224:227], v[184:187], v[76:79]
	v_mfma_f32_16x16x32_bf16 v[72:75], v[216:219], v[192:195], v[72:75]
	v_mfma_f32_16x16x32_bf16 v[68:71], v[224:227], v[192:195], v[68:71]
	v_mfma_f32_16x16x32_bf16 v[116:119], v[220:223], v[172:175], v[116:119]
	v_mfma_f32_16x16x32_bf16 v[108:111], v[228:231], v[172:175], v[108:111]
	v_mfma_f32_16x16x32_bf16 v[100:103], v[220:223], v[180:183], v[100:103]
	v_mfma_f32_16x16x32_bf16 v[92:95], v[228:231], v[180:183], v[92:95]
	v_mfma_f32_16x16x32_bf16 v[84:87], v[220:223], v[188:191], v[84:87]
	v_mfma_f32_16x16x32_bf16 v[76:79], v[228:231], v[188:191], v[76:79]
	v_mfma_f32_16x16x32_bf16 v[72:75], v[220:223], v[212:215], v[72:75]
	v_mfma_f32_16x16x32_bf16 v[68:71], v[228:231], v[212:215], v[68:71]
	s_setprio 0
	s_mov_b32 m0, s24
	v_lshl_add_u64 v[232:233], s[16:17], 0, v[136:137]
	s_barrier
	ds_read_b128 v[168:171], v146 offset:16384
	ds_read_b128 v[172:175], v146 offset:17408
	ds_read_b128 v[176:179], v146 offset:18432
	ds_read_b128 v[180:183], v146 offset:19456
	ds_read_b128 v[184:187], v146 offset:20480
	ds_read_b128 v[188:191], v146 offset:21504
	ds_read_b128 v[192:195], v146 offset:22528
	ds_read_b128 v[212:215], v146 offset:23552
	global_load_lds_dwordx4 v[232:233], off
	v_lshl_add_u64 v[234:235], s[16:17], 0, v[132:133]
	s_mov_b32 m0, s25
	s_nop 0
	global_load_lds_dwordx4 v[234:235], off
	s_add_u32 s40, s14, 0x80000
	s_addc_u32 s41, s15, 0
	s_add_i32 s42, s42, s19
	v_lshl_add_u64 v[246:247], s[40:41], 0, v[134:135]
	s_mov_b32 m0, s42
	s_nop 0
	global_load_lds_dwordx4 v[246:247], off
	v_lshl_add_u64 v[246:247], s[40:41], 0, v[0:1]
	s_add_i32 m0, s42, 0x2000
	s_nop 0
	global_load_lds_dwordx4 v[246:247], off
	s_waitcnt vmcnt(8)
	s_waitcnt lgkmcnt(0)
	s_barrier
; #define PG8_WAIT_V(n) asm volatile("s_waitcnt vmcnt(" #n ")" ::: "memory")
; #define PG8_WAIT_L(n) asm volatile("s_waitcnt lgkmcnt(" #n ")" ::: "memory")
; #define PG8_BAR __builtin_amdgcn_s_barrier()
; #define PG8_SCHED __builtin_amdgcn_sched_barrier(0)
; template <class Epi, class AddrA, class AddrB>
; __device__ __forceinline__ void gemm_phase(const Sched S, const int lda, const int ldb, const int K, const AddrA addrA,
;                                            const AddrB addrB, const Epi E) {
;     ...
;       PG8_BAR; PG8_WAIT_L(0); PG8_MMA(1, 0, At, B0); PG8_BAR; PG8_SCHED;
;       PG8_STAGE(PG8_SB(0, 1), b2 + hstepB, voffB);
;       PG8_WAIT_V(6); PG8_BAR; PG8_MMA(1, 1, At, B1); PG8_BAR;
;       PG8_LDB(B0, 1, 0); PG8_SCHED; PG8_LDA(At, 1, 0); PG8_STAGE(PG8_SA(0, 1), a2 + hstepA, voffA);
;       PG8_WAIT_L(8); PG8_BAR; PG8_WAIT_L(0); PG8_MMA(0, 0, At, B0); PG8_BAR; PG8_SCHED;
;       PG8_LDB(B1, 1, 1); PG8_STAGE(PG8_SB(1, 0), b3, voffB);
;       PG8_BAR; PG8_WAIT_L(0); PG8_MMA(0, 1, At, B1); PG8_BAR;
;       PG8_LDA(At, 1, 1); PG8_STAGE(PG8_SA(1, 0), a3, voffA);
;       PG8_BAR; PG8_WAIT_L(0); PG8_MMA(1, 0, At, B0); PG8_BAR; PG8_SCHED;
	s_waitcnt lgkmcnt(0)
	s_setprio 1
	s_waitcnt lgkmcnt(0)
	v_mfma_f32_16x16x32_bf16 v[64:67], v[148:151], v[168:171], v[64:67]
	v_mfma_f32_16x16x32_bf16 v[60:63], v[156:159], v[168:171], v[60:63]
	v_mfma_f32_16x16x32_bf16 v[56:59], v[148:151], v[176:179], v[56:59]
	v_mfma_f32_16x16x32_bf16 v[48:51], v[156:159], v[176:179], v[48:51]
	v_mfma_f32_16x16x32_bf16 v[40:43], v[148:151], v[184:187], v[40:43]
	v_mfma_f32_16x16x32_bf16 v[32:35], v[156:159], v[184:187], v[32:35]
	v_mfma_f32_16x16x32_bf16 v[24:27], v[148:151], v[192:195], v[24:27]
	v_mfma_f32_16x16x32_bf16 v[16:19], v[156:159], v[192:195], v[16:19]
	v_mfma_f32_16x16x32_bf16 v[64:67], v[152:155], v[172:175], v[64:67]
	v_mfma_f32_16x16x32_bf16 v[60:63], v[160:163], v[172:175], v[60:63]
	v_mfma_f32_16x16x32_bf16 v[56:59], v[152:155], v[180:183], v[56:59]
	v_mfma_f32_16x16x32_bf16 v[48:51], v[160:163], v[180:183], v[48:51]
	v_mfma_f32_16x16x32_bf16 v[40:43], v[152:155], v[188:191], v[40:43]
	v_mfma_f32_16x16x32_bf16 v[32:35], v[160:163], v[188:191], v[32:35]
	v_mfma_f32_16x16x32_bf16 v[24:27], v[152:155], v[212:215], v[24:27]
	v_mfma_f32_16x16x32_bf16 v[16:19], v[160:163], v[212:215], v[16:19]
	v_mfma_f32_16x16x32_bf16 v[52:55], v[216:219], v[168:171], v[52:55]
	v_mfma_f32_16x16x32_bf16 v[44:47], v[224:227], v[168:171], v[44:47]
	v_mfma_f32_16x16x32_bf16 v[36:39], v[216:219], v[176:179], v[36:39]
	v_mfma_f32_16x16x32_bf16 v[28:31], v[224:227], v[176:179], v[28:31]
	v_mfma_f32_16x16x32_bf16 v[20:23], v[216:219], v[184:187], v[20:23]
	v_mfma_f32_16x16x32_bf16 v[12:15], v[224:227], v[184:187], v[12:15]
	v_mfma_f32_16x16x32_bf16 v[8:11], v[216:219], v[192:195], v[8:11]
	v_mfma_f32_16x16x32_bf16 v[4:7], v[224:227], v[192:195], v[4:7]
	v_mfma_f32_16x16x32_bf16 v[52:55], v[220:223], v[172:175], v[52:55]
	v_mfma_f32_16x16x32_bf16 v[44:47], v[228:231], v[172:175], v[44:47]
	v_mfma_f32_16x16x32_bf16 v[36:39], v[220:223], v[180:183], v[36:39]
	v_mfma_f32_16x16x32_bf16 v[28:31], v[228:231], v[180:183], v[28:31]
	v_mfma_f32_16x16x32_bf16 v[20:23], v[220:223], v[188:191], v[20:23]
	v_mfma_f32_16x16x32_bf16 v[12:15], v[228:231], v[188:191], v[12:15]
	v_mfma_f32_16x16x32_bf16 v[8:11], v[220:223], v[212:215], v[8:11]
	v_mfma_f32_16x16x32_bf16 v[4:7], v[228:231], v[212:215], v[4:7]
	s_setprio 0
	s_add_i32 s40, 0, 0x18000
	v_add_u32_e32 v147, s40, v145
	s_barrier
	ds_read_b128 v[148:151], v147
	ds_read_b128 v[152:155], v147 offset:1024
	ds_read_b128 v[156:159], v147 offset:2048
	ds_read_b128 v[160:163], v147 offset:3072
	s_add_u32 s16, s16, 0x80000
	s_addc_u32 s17, s17, 0
	s_mov_b32 m0, s26
	v_lshl_add_u64 v[216:217], s[16:17], 0, v[136:137]
	ds_read_b128 v[168:171], v146 offset:32768
	ds_read_b128 v[172:175], v146 offset:33792
	ds_read_b128 v[176:179], v146 offset:34816
	ds_read_b128 v[180:183], v146 offset:35840
	ds_read_b128 v[184:187], v146 offset:36864
	ds_read_b128 v[188:191], v146 offset:37888
	ds_read_b128 v[192:195], v146 offset:38912
	ds_read_b128 v[212:215], v146 offset:39936
	global_load_lds_dwordx4 v[216:217], off
	v_lshl_add_u64 v[216:217], s[16:17], 0, v[132:133]
	s_mov_b32 m0, s27
	s_nop 0
	global_load_lds_dwordx4 v[216:217], off
	s_waitcnt lgkmcnt(8)
	s_barrier
	s_waitcnt lgkmcnt(0)
	s_setprio 1
	s_waitcnt lgkmcnt(0)
	v_mfma_f32_16x16x32_bf16 v[128:131], v[148:151], v[168:171], v[128:131]
	v_mfma_f32_16x16x32_bf16 v[124:127], v[156:159], v[168:171], v[124:127]
	v_mfma_f32_16x16x32_bf16 v[120:123], v[148:151], v[176:179], v[120:123]
	v_mfma_f32_16x16x32_bf16 v[112:115], v[156:159], v[176:179], v[112:115]
	v_mfma_f32_16x16x32_bf16 v[104:107], v[148:151], v[184:187], v[104:107]
	v_mfma_f32_16x16x32_bf16 v[96:99], v[156:159], v[184:187], v[96:99]
	v_mfma_f32_16x16x32_bf16 v[88:91], v[148:151], v[192:195], v[88:91]
	v_mfma_f32_16x16x32_bf16 v[80:83], v[156:159], v[192:195], v[80:83]
	v_mfma_f32_16x16x32_bf16 v[128:131], v[152:155], v[172:175], v[128:131]
	v_mfma_f32_16x16x32_bf16 v[124:127], v[160:163], v[172:175], v[124:127]
	v_mfma_f32_16x16x32_bf16 v[120:123], v[152:155], v[180:183], v[120:123]
	v_mfma_f32_16x16x32_bf16 v[112:115], v[160:163], v[180:183], v[112:115]
	v_mfma_f32_16x16x32_bf16 v[104:107], v[152:155], v[188:191], v[104:107]
	v_mfma_f32_16x16x32_bf16 v[96:99], v[160:163], v[188:191], v[96:99]
	v_mfma_f32_16x16x32_bf16 v[88:91], v[152:155], v[212:215], v[88:91]
	v_mfma_f32_16x16x32_bf16 v[80:83], v[160:163], v[212:215], v[80:83]
	s_setprio 0
	s_barrier
	s_add_i32 s16, 0, 0x1c000
	s_add_i32 s17, s40, s19
	v_add_u32_e32 v147, s16, v145
	v_lshl_add_u64 v[142:143], v[142:143], 0, s[52:53]
	s_mov_b32 m0, s17
	ds_read_b128 v[216:219], v147
	ds_read_b128 v[220:223], v147 offset:1024
	ds_read_b128 v[224:227], v147 offset:2048
	ds_read_b128 v[228:231], v147 offset:3072
	global_load_lds_dwordx4 v[142:143], off
	v_lshl_add_u64 v[142:143], v[196:197], 0, s[52:53]
	s_add_i32 m0, s17, 0x2000
	s_nop 0
	global_load_lds_dwordx4 v[142:143], off
	s_waitcnt vmcnt(10)
	s_waitcnt lgkmcnt(0)
	s_barrier
	s_waitcnt lgkmcnt(0)
	s_setprio 1
	s_waitcnt lgkmcnt(0)
	v_mfma_f32_16x16x32_bf16 v[116:119], v[216:219], v[168:171], v[116:119]
	v_mfma_f32_16x16x32_bf16 v[108:111], v[224:227], v[168:171], v[108:111]
	v_mfma_f32_16x16x32_bf16 v[100:103], v[216:219], v[176:179], v[100:103]
	v_mfma_f32_16x16x32_bf16 v[92:95], v[224:227], v[176:179], v[92:95]
	v_mfma_f32_16x16x32_bf16 v[84:87], v[216:219], v[184:187], v[84:87]
	v_mfma_f32_16x16x32_bf16 v[76:79], v[224:227], v[184:187], v[76:79]
	v_mfma_f32_16x16x32_bf16 v[72:75], v[216:219], v[192:195], v[72:75]
	v_mfma_f32_16x16x32_bf16 v[68:71], v[224:227], v[192:195], v[68:71]
	v_mfma_f32_16x16x32_bf16 v[116:119], v[220:223], v[172:175], v[116:119]
	v_mfma_f32_16x16x32_bf16 v[108:111], v[228:231], v[172:175], v[108:111]
	v_mfma_f32_16x16x32_bf16 v[100:103], v[220:223], v[180:183], v[100:103]
	v_mfma_f32_16x16x32_bf16 v[92:95], v[228:231], v[180:183], v[92:95]
	v_mfma_f32_16x16x32_bf16 v[84:87], v[220:223], v[188:191], v[84:87]
	v_mfma_f32_16x16x32_bf16 v[76:79], v[228:231], v[188:191], v[76:79]
	v_mfma_f32_16x16x32_bf16 v[72:75], v[220:223], v[212:215], v[72:75]
	v_mfma_f32_16x16x32_bf16 v[68:71], v[228:231], v[212:215], v[68:71]
	s_setprio 0
	s_mov_b32 m0, s30
	v_lshl_add_u64 v[142:143], v[232:233], 0, s[52:53]
	s_barrier
; #define PG8_WAIT_V(n) asm volatile("s_waitcnt vmcnt(" #n ")" ::: "memory")
; #define PG8_WAIT_L(n) asm volatile("s_waitcnt lgkmcnt(" #n ")" ::: "memory")
; #define PG8_BAR __builtin_amdgcn_s_barrier()
; #define PG8_SCHED __builtin_amdgcn_sched_barrier(0)
; template <class Epi, class AddrA, class AddrB>
; __device__ __forceinline__ void gemm_phase(const Sched S, const int lda, const int ldb, const int K, const AddrA addrA,
;                                            const AddrB addrB, const Epi E) {
;     ...
;       PG8_BAR; PG8_WAIT_L(0); PG8_MMA(1, 0, At, B0); PG8_BAR; PG8_SCHED;
;       PG8_STAGE(PG8_SB(1, 1), b3 + hstepB, voffB);
;       PG8_WAIT_V(6); PG8_BAR; PG8_MMA(1, 1, At, B1); PG8_BAR;
;     }
	ds_read_b128 v[168:171], v146 offset:49152
	ds_read_b128 v[172:175], v146 offset:50176
	ds_read_b128 v[176:179], v146 offset:51200
	ds_read_b128 v[180:183], v146 offset:52224
	ds_read_b128 v[184:187], v146 offset:53248
	ds_read_b128 v[188:191], v146 offset:54272
	ds_read_b128 v[192:195], v146 offset:55296
	ds_read_b128 v[212:215], v146 offset:56320
	global_load_lds_dwordx4 v[142:143], off
	v_lshl_add_u64 v[142:143], v[234:235], 0, s[52:53]
	s_mov_b32 m0, s31
	s_nop 0
	global_load_lds_dwordx4 v[142:143], off
	s_add_u32 s14, s14, 0x80080
	s_addc_u32 s15, s15, 0
	s_add_i32 s16, s16, s19
	v_lshl_add_u64 v[142:143], s[14:15], 0, v[134:135]
	s_mov_b32 m0, s16
	s_nop 0
	global_load_lds_dwordx4 v[142:143], off
	v_lshl_add_u64 v[142:143], s[14:15], 0, v[0:1]
	s_add_i32 m0, s16, 0x2000
	s_nop 0
	global_load_lds_dwordx4 v[142:143], off
	s_waitcnt vmcnt(8)
	s_waitcnt lgkmcnt(0)
	s_barrier
	s_waitcnt lgkmcnt(0)
	s_setprio 1
	s_waitcnt lgkmcnt(0)
	v_mfma_f32_16x16x32_bf16 v[64:67], v[148:151], v[168:171], v[64:67]
	v_mfma_f32_16x16x32_bf16 v[60:63], v[156:159], v[168:171], v[60:63]
	v_mfma_f32_16x16x32_bf16 v[56:59], v[148:151], v[176:179], v[56:59]
	v_mfma_f32_16x16x32_bf16 v[48:51], v[156:159], v[176:179], v[48:51]
	v_mfma_f32_16x16x32_bf16 v[40:43], v[148:151], v[184:187], v[40:43]
	v_mfma_f32_16x16x32_bf16 v[32:35], v[156:159], v[184:187], v[32:35]
	v_mfma_f32_16x16x32_bf16 v[24:27], v[148:151], v[192:195], v[24:27]
	v_mfma_f32_16x16x32_bf16 v[16:19], v[156:159], v[192:195], v[16:19]
	v_mfma_f32_16x16x32_bf16 v[64:67], v[152:155], v[172:175], v[64:67]
	v_mfma_f32_16x16x32_bf16 v[60:63], v[160:163], v[172:175], v[60:63]
	v_mfma_f32_16x16x32_bf16 v[56:59], v[152:155], v[180:183], v[56:59]
	v_mfma_f32_16x16x32_bf16 v[48:51], v[160:163], v[180:183], v[48:51]
	v_mfma_f32_16x16x32_bf16 v[40:43], v[152:155], v[188:191], v[40:43]
	v_mfma_f32_16x16x32_bf16 v[32:35], v[160:163], v[188:191], v[32:35]
	v_mfma_f32_16x16x32_bf16 v[24:27], v[152:155], v[212:215], v[24:27]
	v_mfma_f32_16x16x32_bf16 v[16:19], v[160:163], v[212:215], v[16:19]
	v_mfma_f32_16x16x32_bf16 v[52:55], v[216:219], v[168:171], v[52:55]
	v_mfma_f32_16x16x32_bf16 v[44:47], v[224:227], v[168:171], v[44:47]
	v_mfma_f32_16x16x32_bf16 v[36:39], v[216:219], v[176:179], v[36:39]
	v_mfma_f32_16x16x32_bf16 v[28:31], v[224:227], v[176:179], v[28:31]
	v_mfma_f32_16x16x32_bf16 v[20:23], v[216:219], v[184:187], v[20:23]
	v_mfma_f32_16x16x32_bf16 v[12:15], v[224:227], v[184:187], v[12:15]
	v_mfma_f32_16x16x32_bf16 v[8:11], v[216:219], v[192:195], v[8:11]
	v_mfma_f32_16x16x32_bf16 v[4:7], v[224:227], v[192:195], v[4:7]
	v_mfma_f32_16x16x32_bf16 v[52:55], v[220:223], v[172:175], v[52:55]
	v_mfma_f32_16x16x32_bf16 v[44:47], v[228:231], v[172:175], v[44:47]
	v_mfma_f32_16x16x32_bf16 v[36:39], v[220:223], v[180:183], v[36:39]
	v_mfma_f32_16x16x32_bf16 v[28:31], v[228:231], v[180:183], v[28:31]
	v_mfma_f32_16x16x32_bf16 v[20:23], v[220:223], v[188:191], v[20:23]
	v_mfma_f32_16x16x32_bf16 v[12:15], v[228:231], v[188:191], v[12:15]
	v_mfma_f32_16x16x32_bf16 v[8:11], v[220:223], v[212:215], v[8:11]
	v_mfma_f32_16x16x32_bf16 v[4:7], v[228:231], v[212:215], v[4:7]
	s_setprio 0
	s_add_i32 s39, s39, 2
	s_add_u32 s37, s37, 0x100
	s_addc_u32 s38, s38, 0
	s_add_u32 s12, s12, 0x100
	s_addc_u32 s13, s13, 0
	s_cmp_gt_u32 s39, 29
	s_barrier
	s_cbranch_scc0 .LBB0_109
; template <class Epi, class AddrA, class AddrB>
; __device__ __forceinline__ void gemm_phase(const Sched S, const int lda, const int ldb, const int K, const AddrA addrA,
;                                            const AddrB addrB, const Epi E) {
;     ...
;     E(acc, cur, wr, wc, fr, fq);
;     if (!has_next) break;
;     if (!(Epi::KEEP && cur.br + 1 < S.nbr)) {
; #pragma unroll
;       for (int a = 0; a < 2; ++a)
; #pragma unroll
;         for (int b = 0; b < 2; ++b)
; #pragma unroll
;           for (int m = 0; m < 4; ++m)
; #pragma unroll
;             for (int n = 0; n < 2; ++n) acc[a][b][m][n] = (f32x4){0.f, 0.f, 0.f, 0.f};
;     }
;     cur = nxt; cA = nA; cB = nB; ++ui;
;   __device__ __forceinline__ void operator()(EPI_ARGS) const {
;     bf16_t* base = proj + ((size_t)u.pn * MTOK + (size_t)(u.pm * 256 + wr * 64 + fr)) * PLD + wc * 32 + 8 * fq;
; #pragma unroll
;     for (int ai = 0; ai < 2; ++ai)
; #pragma unroll
;       for (int m = 0; m < 4; ++m) {
;         bf16_t* rowp = base + (size_t)(ai * HALF + m * 16) * PLD;
; #pragma unroll
;         for (int bj = 0; bj < 2; ++bj) {
;           const f32x4 v0 = acc[ai][bj][m][0], v1 = acc[ai][bj][m][1];
;           u32x4 o;
;           o.x = pack2(v0[0], v0[1]); o.y = pack2(v0[2], v0[3]); o.z = pack2(v1[0], v1[1]); o.w = pack2(v1[2], v1[3]);
;           *(u32x4*)(rowp + bj * HALF) = o;
;         }
;       }
;   }
	s_ashr_i32 s11, s10, 31
	v_lshl_add_u32 v142, s35, 8, v144
	s_lshl_b64 s[10:11], s[10:11], 23
	v_ashrrev_i32_e32 v143, 31, v142
	s_add_u32 s10, s28, s10
	s_addc_u32 s11, s29, s11
	v_lshlrev_b64 v[142:143], 9, v[142:143]
	v_lshl_add_u64 v[142:143], s[10:11], 0, v[142:143]
	v_lshl_add_u64 v[142:143], v[142:143], 0, s[72:73]
	v_lshl_add_u64 v[142:143], v[142:143], 0, v[2:3]
	v_cvt_pk_bf16_f32 v116, v116, v117
	v_cvt_pk_bf16_f32 v117, v118, v119
	v_cvt_pk_bf16_f32 v119, v110, v111
	v_cvt_pk_bf16_f32 v110, v112, v113
	v_add_co_u32_e32 v112, vcc, s96, v142
	s_movk_i32 s1, 0x4000
	s_nop 0
	v_addc_co_u32_e32 v113, vcc, 0, v143, vcc
	v_cvt_pk_bf16_f32 v100, v100, v101
	v_cvt_pk_bf16_f32 v101, v102, v103
	v_cvt_pk_bf16_f32 v103, v94, v95
	v_cvt_pk_bf16_f32 v94, v96, v97
	v_add_co_u32_e32 v96, vcc, s1, v142
	s_movk_i32 s1, 0x6000
	s_nop 0
	v_addc_co_u32_e32 v97, vcc, 0, v143, vcc
	v_cvt_pk_bf16_f32 v84, v84, v85
	v_cvt_pk_bf16_f32 v85, v86, v87
	v_cvt_pk_bf16_f32 v87, v78, v79
	v_cvt_pk_bf16_f32 v78, v80, v81
	v_add_co_u32_e32 v80, vcc, s1, v142
	v_cvt_pk_bf16_f32 v64, v64, v65
	v_cvt_pk_bf16_f32 v65, v66, v67
	v_cvt_pk_bf16_f32 v66, v60, v61
	s_mov_b32 s1, 0x12000
	s_nop 0
	v_addc_co_u32_e32 v81, vcc, 0, v143, vcc
	v_add_co_u32_e32 v60, vcc, s67, v142
	v_cvt_pk_bf16_f32 v52, v52, v53
	v_cvt_pk_bf16_f32 v53, v54, v55
	v_cvt_pk_bf16_f32 v55, v46, v47
	v_cvt_pk_bf16_f32 v46, v48, v49
	s_nop 1
	v_addc_co_u32_e32 v61, vcc, 0, v143, vcc
	v_add_co_u32_e32 v48, vcc, s1, v142
	s_mov_b32 s1, 0x14000
	s_nop 0
	v_addc_co_u32_e32 v49, vcc, 0, v143, vcc
	v_cvt_pk_bf16_f32 v36, v36, v37
	v_cvt_pk_bf16_f32 v37, v38, v39
	v_cvt_pk_bf16_f32 v39, v30, v31
	v_cvt_pk_bf16_f32 v30, v32, v33
	v_add_co_u32_e32 v32, vcc, s1, v142
	s_mov_b32 s1, 0x16000
	s_nop 0
	v_addc_co_u32_e32 v33, vcc, 0, v143, vcc
	v_cvt_pk_bf16_f32 v20, v20, v21
	v_cvt_pk_bf16_f32 v21, v22, v23
	v_cvt_pk_bf16_f32 v23, v14, v15
	v_cvt_pk_bf16_f32 v14, v16, v17
	v_add_co_u32_e32 v16, vcc, s1, v142
	s_mov_b32 s10, s2
	s_nop 0
	v_addc_co_u32_e32 v17, vcc, 0, v143, vcc
	s_and_b64 vcc, exec, s[4:5]
	s_mov_b32 s35, s0
	s_mov_b64 s[12:13], s[8:9]
	s_mov_b64 s[14:15], s[6:7]
	v_cvt_pk_bf16_f32 v128, v128, v129
	v_cvt_pk_bf16_f32 v129, v130, v131
	v_cvt_pk_bf16_f32 v130, v124, v125
	v_cvt_pk_bf16_f32 v131, v126, v127
	flat_store_dwordx4 v[142:143], v[128:131]
	v_cvt_pk_bf16_f32 v118, v108, v109
	flat_store_dwordx4 v[142:143], v[116:119] offset:256
	v_cvt_pk_bf16_f32 v108, v120, v121
	v_cvt_pk_bf16_f32 v109, v122, v123
	v_cvt_pk_bf16_f32 v111, v114, v115
	flat_store_dwordx4 v[112:113], v[108:111]
	v_cvt_pk_bf16_f32 v102, v92, v93
	flat_store_dwordx4 v[112:113], v[100:103] offset:256
	v_cvt_pk_bf16_f32 v92, v104, v105
	v_cvt_pk_bf16_f32 v93, v106, v107
	v_cvt_pk_bf16_f32 v95, v98, v99
	flat_store_dwordx4 v[96:97], v[92:95]
	v_cvt_pk_bf16_f32 v86, v76, v77
	flat_store_dwordx4 v[96:97], v[84:87] offset:256
	v_cvt_pk_bf16_f32 v76, v88, v89
	v_cvt_pk_bf16_f32 v77, v90, v91
	v_cvt_pk_bf16_f32 v79, v82, v83
	flat_store_dwordx4 v[80:81], v[76:79]
	v_cvt_pk_bf16_f32 v72, v72, v73
	v_cvt_pk_bf16_f32 v73, v74, v75
	v_cvt_pk_bf16_f32 v74, v68, v69
	v_cvt_pk_bf16_f32 v75, v70, v71
	flat_store_dwordx4 v[80:81], v[72:75] offset:256
	v_cvt_pk_bf16_f32 v67, v62, v63
	flat_store_dwordx4 v[60:61], v[64:67]
	v_cvt_pk_bf16_f32 v54, v44, v45
	flat_store_dwordx4 v[60:61], v[52:55] offset:256
	v_cvt_pk_bf16_f32 v44, v56, v57
	v_cvt_pk_bf16_f32 v45, v58, v59
	v_cvt_pk_bf16_f32 v47, v50, v51
	flat_store_dwordx4 v[48:49], v[44:47]
	v_cvt_pk_bf16_f32 v38, v28, v29
	flat_store_dwordx4 v[48:49], v[36:39] offset:256
	v_cvt_pk_bf16_f32 v28, v40, v41
	v_cvt_pk_bf16_f32 v29, v42, v43
	v_cvt_pk_bf16_f32 v31, v34, v35
	flat_store_dwordx4 v[32:33], v[28:31]
	v_cvt_pk_bf16_f32 v22, v12, v13
	flat_store_dwordx4 v[32:33], v[20:23] offset:256
	v_cvt_pk_bf16_f32 v12, v24, v25
	v_cvt_pk_bf16_f32 v13, v26, v27
	v_cvt_pk_bf16_f32 v15, v18, v19
	flat_store_dwordx4 v[16:17], v[12:15]
	v_cvt_pk_bf16_f32 v8, v8, v9
	v_cvt_pk_bf16_f32 v9, v10, v11
	v_cvt_pk_bf16_f32 v10, v4, v5
	v_cvt_pk_bf16_f32 v11, v6, v7
	flat_store_dwordx4 v[16:17], v[8:11] offset:256
	s_cbranch_vccz .LBB0_106
	s_waitcnt vmcnt(0)
	s_cmpk_gt_u32 s18, 0xff
	s_cbranch_scc1 .LBB0_113
	s_barrier

; __global__ void __launch_bounds__(512) fwd_megakernel(Params p) {
	.amdhsa_kernel _Z14fwd_megakernel6Params
		.amdhsa_group_segment_fixed_size 0
		.amdhsa_private_segment_fixed_size 0
		.amdhsa_kernarg_size 416
		.amdhsa_user_sgpr_count 2
		.amdhsa_user_sgpr_dispatch_ptr 0
		.amdhsa_user_sgpr_queue_ptr 0
		.amdhsa_user_sgpr_kernarg_segment_ptr 1
		.amdhsa_user_sgpr_dispatch_id 0
		.amdhsa_user_sgpr_kernarg_preload_length 0
		.amdhsa_user_sgpr_kernarg_preload_offset 0
		.amdhsa_user_sgpr_private_segment_size 0
		.amdhsa_uses_dynamic_stack 0
		.amdhsa_enable_private_segment 0
		.amdhsa_system_sgpr_workgroup_id_x 1
		.amdhsa_system_sgpr_workgroup_id_y 0
		.amdhsa_system_sgpr_workgroup_id_z 0
		.amdhsa_system_sgpr_workgroup_info 0
		.amdhsa_system_vgpr_workitem_id 2
		.amdhsa_next_free_vgpr 248
		.amdhsa_next_free_sgpr 98
		.amdhsa_accum_offset 248
		.amdhsa_reserve_vcc 1
		.amdhsa_float_round_mode_32 0
		.amdhsa_float_round_mode_16_64 0
		.amdhsa_float_denorm_mode_32 3
		.amdhsa_float_denorm_mode_16_64 3
		.amdhsa_dx10_clamp 1
		.amdhsa_ieee_mode 1
		.amdhsa_fp16_overflow 0
		.amdhsa_tg_split 0
		.amdhsa_exception_fp_ieee_invalid_op 0
		.amdhsa_exception_fp_denorm_src 0
		.amdhsa_exception_fp_ieee_div_zero 0
		.amdhsa_exception_fp_ieee_overflow 0
		.amdhsa_exception_fp_ieee_underflow 0
		.amdhsa_exception_fp_ieee_inexact 0
		.amdhsa_exception_int_div_zero 0
	.end_amdhsa_kernel

; __global__ void __launch_bounds__(512) fwd_megakernel(Params p) {
amdhsa.kernels:
  - .agpr_count:     0
    .args:
      - .offset:         0
        .size:           160
        .value_kind:     by_value
      - .offset:         160
        .size:           4
        .value_kind:     hidden_block_count_x
      - .offset:         164
        .size:           4
        .value_kind:     hidden_block_count_y
      - .offset:         168
        .size:           4
        .value_kind:     hidden_block_count_z
      - .offset:         172
        .size:           2
        .value_kind:     hidden_group_size_x
      - .offset:         174
        .size:           2
        .value_kind:     hidden_group_size_y
      - .offset:         176
        .size:           2
        .value_kind:     hidden_group_size_z
      - .offset:         178
        .size:           2
        .value_kind:     hidden_remainder_x
      - .offset:         180
        .size:           2
        .value_kind:     hidden_remainder_y
      - .offset:         182
        .size:           2
        .value_kind:     hidden_remainder_z
      - .offset:         200
        .size:           8
        .value_kind:     hidden_global_offset_x
      - .offset:         208
        .size:           8
        .value_kind:     hidden_global_offset_y
      - .offset:         216
        .size:           8
        .value_kind:     hidden_global_offset_z
      - .offset:         224
        .size:           2
        .value_kind:     hidden_grid_dims
      - .offset:         248
        .size:           8
        .value_kind:     hidden_multigrid_sync_arg
      - .offset:         280
        .size:           4
        .value_kind:     hidden_dynamic_lds_size
    .group_segment_fixed_size: 0
    .kernarg_segment_align: 8
    .kernarg_segment_size: 416
    .language:       OpenCL C
    .language_version:
      - 2
      - 0
    .max_flat_workgroup_size: 512
    .name:           _Z14fwd_megakernel6Params
    .private_segment_fixed_size: 0
    .sgpr_count:     104
    .sgpr_spill_count: 156
    .symbol:         _Z14fwd_megakernel6Params.kd
    .uniform_work_group_size: 1
    .uses_dynamic_stack: false
    .vgpr_count:     248
    .vgpr_spill_count: 0
    .wavefront_size: 64
